# P0 Ktab reduction loop software-pipelined with two register sets (next pass's loads issued before this pass's arithmetic)
# speedup vs baseline: 1.0274x; 1.0037x over previous
; DI float2 cmul(float2 a, float2 b) { return make_float2(a.x * b.x - a.y * b.y, a.x * b.y + a.y * b.x); }
; DI void phase0(const Params& P, char* smem) {
;     ...
;       int h = tid >> 4, hp = tid & 15;
;       float s = 0.f;
;       for (int p = 0; p < 64; ++p) {
;         float2 T = cmul(Es[p], make_float2(P.b_re[(g * 64 + p) * 16 + hp], P.b_im[(g * 64 + p) * 16 + hp]));
;         s += P.c_re[(g * 16 + h) * 64 + p] * T.x - P.c_im[(g * 16 + h) * 64 + p] * T.y;
;       }
;       Ktab[((g * 64 + d) * 16 + h) * 16 + hp] = s;
.LBB0_46:
	s_or_b64 exec, exec, s[18:19]
	v_lshl_or_b32 v2, v2, 10, v9
	v_ashrrev_i32_e32 v3, 31, v2
	v_readlane_b32 s36, v254, 16
	v_lshlrev_b32_e32 v0, 4, v16
	v_lshlrev_b64 v[6:7], 2, v[2:3]
	v_readlane_b32 s37, v254, 17
	v_and_or_b32 v4, v0, s69, v188
	v_lshl_add_u64 v[2:3], s[66:67], 0, v[6:7]
	v_lshl_add_u64 v[6:7], s[36:37], 0, v[6:7]
	v_mov_b32_e32 v0, 0
	s_mov_b64 s[0:1], 0
	v_mov_b32_e32 v18, v192
	s_waitcnt lgkmcnt(0)
	s_barrier
	v_readlane_b32 s38, v254, 18
	v_readlane_b32 s39, v254, 19
	v_readlane_b32 s40, v254, 20
	v_readlane_b32 s41, v254, 21
	v_readlane_b32 s42, v254, 22
	v_readlane_b32 s43, v254, 23
	v_readlane_b32 s44, v254, 24
	v_readlane_b32 s45, v254, 25
	v_readlane_b32 s46, v254, 26
	v_readlane_b32 s47, v254, 27
	v_readlane_b32 s48, v254, 28
	v_readlane_b32 s49, v254, 29
	v_readlane_b32 s50, v254, 30
	v_readlane_b32 s51, v254, 31
	v_ashrrev_i32_e32 v5, 31, v4
	v_lshlrev_b64 v[34:35], 2, v[4:5]
	v_lshl_add_u64 v[20:21], v[2:3], 0, s[0:1]
	v_lshl_add_u64 v[24:25], v[6:7], 0, s[0:1]
	v_lshl_add_u64 v[36:37], s[62:63], 0, v[34:35]
	v_add_u32_e32 v28, 16, v4
	v_add_u32_e32 v30, 32, v4
	v_add_u32_e32 v32, 48, v4
	global_load_dwordx4 v[20:23], v[20:21], off
	s_nop 0
	global_load_dwordx4 v[24:27], v[24:25], off
	v_lshl_add_u64 v[34:35], s[64:65], 0, v[34:35]
	global_load_dword v36, v[36:37], off
	s_nop 0
	global_load_dword v38, v[34:35], off
	v_ashrrev_i32_e32 v29, 31, v28
	v_ashrrev_i32_e32 v31, 31, v30
	v_ashrrev_i32_e32 v33, 31, v32
	v_lshlrev_b64 v[28:29], 2, v[28:29]
	v_lshlrev_b64 v[30:31], 2, v[30:31]
	v_lshlrev_b64 v[32:33], 2, v[32:33]
	v_lshl_add_u64 v[34:35], s[62:63], 0, v[28:29]
	v_lshl_add_u64 v[28:29], s[64:65], 0, v[28:29]
	v_lshl_add_u64 v[40:41], s[62:63], 0, v[30:31]
	v_lshl_add_u64 v[42:43], s[62:63], 0, v[32:33]
	v_lshl_add_u64 v[30:31], s[64:65], 0, v[30:31]
	v_lshl_add_u64 v[32:33], s[64:65], 0, v[32:33]
	global_load_dword v44, v[28:29], off
	global_load_dword v46, v[30:31], off
	global_load_dword v48, v[32:33], off
	global_load_dword v50, v[34:35], off
	s_nop 0
	global_load_dword v40, v[40:41], off
	s_nop 0
	global_load_dword v42, v[42:43], off
	ds_read_b128 v[28:31], v18
	ds_read_b128 v[32:35], v18 offset:16
	s_add_u32 s0, s0, 16
	s_addc_u32 s1, s1, 0
	v_add_u32_e32 v18, 32, v18
	v_add_u32_e32 v4, 64, v4
	s_mov_b32 s32, 7
.Lp0_ktab_loop:
	v_ashrrev_i32_e32 v5, 31, v4
	v_lshlrev_b64 v[158:159], 2, v[4:5]
	v_lshl_add_u64 v[144:145], v[2:3], 0, s[0:1]
	v_lshl_add_u64 v[148:149], v[6:7], 0, s[0:1]
	v_lshl_add_u64 v[160:161], s[62:63], 0, v[158:159]
	v_add_u32_e32 v152, 16, v4
	v_add_u32_e32 v154, 32, v4
	v_add_u32_e32 v156, 48, v4
	global_load_dwordx4 v[144:147], v[144:145], off
	s_nop 0
	global_load_dwordx4 v[148:151], v[148:149], off
	v_lshl_add_u64 v[158:159], s[64:65], 0, v[158:159]
	global_load_dword v160, v[160:161], off
	s_nop 0
	global_load_dword v162, v[158:159], off
	v_ashrrev_i32_e32 v153, 31, v152
	v_ashrrev_i32_e32 v155, 31, v154
	v_ashrrev_i32_e32 v157, 31, v156
	v_lshlrev_b64 v[152:153], 2, v[152:153]
	v_lshlrev_b64 v[154:155], 2, v[154:155]
	v_lshlrev_b64 v[156:157], 2, v[156:157]
	v_lshl_add_u64 v[158:159], s[62:63], 0, v[152:153]
	v_lshl_add_u64 v[152:153], s[64:65], 0, v[152:153]
	v_lshl_add_u64 v[164:165], s[62:63], 0, v[154:155]
	v_lshl_add_u64 v[166:167], s[62:63], 0, v[156:157]
	v_lshl_add_u64 v[154:155], s[64:65], 0, v[154:155]
	v_lshl_add_u64 v[156:157], s[64:65], 0, v[156:157]
	global_load_dword v168, v[152:153], off
	global_load_dword v170, v[154:155], off
	global_load_dword v172, v[156:157], off
	global_load_dword v174, v[158:159], off
	s_nop 0
	global_load_dword v164, v[164:165], off
	s_nop 0
	global_load_dword v166, v[166:167], off
	ds_read_b128 v[152:155], v18
	ds_read_b128 v[156:159], v18 offset:16
	s_add_u32 s0, s0, 16
	s_addc_u32 s1, s1, 0
	v_add_u32_e32 v18, 32, v18
	v_add_u32_e32 v4, 64, v4
	s_waitcnt vmcnt(19)
	v_mov_b32_e32 v52, v20
	s_waitcnt vmcnt(18)
	v_mov_b32_e32 v53, v24
	v_mov_b32_e32 v24, v21
	v_mov_b32_e32 v20, v22
	v_mov_b32_e32 v21, v26
	v_mov_b32_e32 v26, v23
	s_waitcnt vmcnt(16) lgkmcnt(3)
	v_pk_mul_f32 v[22:23], v[28:29], v[38:39] op_sel:[1,0] op_sel_hi:[0,0]
	v_pk_fma_f32 v[38:39], v[28:29], v[36:37], v[22:23] neg_lo:[0,0,1] neg_hi:[0,0,1]
	v_pk_fma_f32 v[22:23], v[28:29], v[36:37], v[22:23] op_sel_hi:[1,0,1]
	s_waitcnt vmcnt(15)
	v_pk_mul_f32 v[28:29], v[30:31], v[44:45] op_sel:[1,0] op_sel_hi:[0,0]
	s_waitcnt vmcnt(14) lgkmcnt(2)
	v_pk_mul_f32 v[36:37], v[32:33], v[46:47] op_sel:[1,0] op_sel_hi:[0,0]
	v_mov_b32_e32 v39, v23
	s_waitcnt vmcnt(12)
	v_pk_fma_f32 v[22:23], v[30:31], v[50:51], v[28:29] neg_lo:[0,0,1] neg_hi:[0,0,1]
	v_pk_fma_f32 v[28:29], v[30:31], v[50:51], v[28:29] op_sel_hi:[1,0,1]
	v_pk_mul_f32 v[44:45], v[34:35], v[48:49] op_sel:[1,0] op_sel_hi:[0,0]
	s_waitcnt vmcnt(11)
	v_pk_fma_f32 v[30:31], v[32:33], v[40:41], v[36:37] neg_lo:[0,0,1] neg_hi:[0,0,1]
	v_pk_fma_f32 v[32:33], v[32:33], v[40:41], v[36:37] op_sel_hi:[1,0,1]
	v_pk_mul_f32 v[38:39], v[52:53], v[38:39]
	v_mov_b32_e32 v23, v29
	s_waitcnt vmcnt(10)
; DI float2 cmul(float2 a, float2 b) { return make_float2(a.x * b.x - a.y * b.y, a.x * b.y + a.y * b.x); }
; DI void phase0(const Params& P, char* smem) {
;     ...
;       int h = tid >> 4, hp = tid & 15;
;       float s = 0.f;
;       for (int p = 0; p < 64; ++p) {
;         float2 T = cmul(Es[p], make_float2(P.b_re[(g * 64 + p) * 16 + hp], P.b_im[(g * 64 + p) * 16 + hp]));
;         s += P.c_re[(g * 16 + h) * 64 + p] * T.x - P.c_im[(g * 16 + h) * 64 + p] * T.y;
;       }
;       Ktab[((g * 64 + d) * 16 + h) * 16 + hp] = s;
	v_pk_fma_f32 v[36:37], v[34:35], v[42:43], v[44:45] neg_lo:[0,0,1] neg_hi:[0,0,1]
	v_pk_fma_f32 v[34:35], v[34:35], v[42:43], v[44:45] op_sel_hi:[1,0,1]
	v_mov_b32_e32 v31, v33
	v_sub_f32_e32 v5, v38, v39
	v_pk_mul_f32 v[22:23], v[24:25], v[22:23]
	v_mov_b32_e32 v37, v35
	v_pk_mul_f32 v[20:21], v[20:21], v[30:31]
	v_add_f32_e32 v0, v0, v5
	v_sub_f32_e32 v5, v22, v23
	v_pk_mul_f32 v[24:25], v[26:27], v[36:37]
	v_sub_f32_e32 v19, v20, v21
	v_add_f32_e32 v0, v0, v5
	v_sub_f32_e32 v20, v24, v25
	v_add_f32_e32 v0, v0, v19
	v_add_f32_e32 v0, v0, v20
	v_ashrrev_i32_e32 v5, 31, v4
	v_lshlrev_b64 v[34:35], 2, v[4:5]
	v_lshl_add_u64 v[20:21], v[2:3], 0, s[0:1]
	v_lshl_add_u64 v[24:25], v[6:7], 0, s[0:1]
	v_lshl_add_u64 v[36:37], s[62:63], 0, v[34:35]
	v_add_u32_e32 v28, 16, v4
	v_add_u32_e32 v30, 32, v4
	v_add_u32_e32 v32, 48, v4
	global_load_dwordx4 v[20:23], v[20:21], off
	s_nop 0
	global_load_dwordx4 v[24:27], v[24:25], off
	v_lshl_add_u64 v[34:35], s[64:65], 0, v[34:35]
	global_load_dword v36, v[36:37], off
	s_nop 0
	global_load_dword v38, v[34:35], off
	v_ashrrev_i32_e32 v29, 31, v28
	v_ashrrev_i32_e32 v31, 31, v30
	v_ashrrev_i32_e32 v33, 31, v32
	v_lshlrev_b64 v[28:29], 2, v[28:29]
	v_lshlrev_b64 v[30:31], 2, v[30:31]
	v_lshlrev_b64 v[32:33], 2, v[32:33]
	v_lshl_add_u64 v[34:35], s[62:63], 0, v[28:29]
	v_lshl_add_u64 v[28:29], s[64:65], 0, v[28:29]
	v_lshl_add_u64 v[40:41], s[62:63], 0, v[30:31]
	v_lshl_add_u64 v[42:43], s[62:63], 0, v[32:33]
	v_lshl_add_u64 v[30:31], s[64:65], 0, v[30:31]
	v_lshl_add_u64 v[32:33], s[64:65], 0, v[32:33]
	global_load_dword v44, v[28:29], off
	global_load_dword v46, v[30:31], off
	global_load_dword v48, v[32:33], off
	global_load_dword v50, v[34:35], off
	s_nop 0
	global_load_dword v40, v[40:41], off
	s_nop 0
	global_load_dword v42, v[42:43], off
	ds_read_b128 v[28:31], v18
	ds_read_b128 v[32:35], v18 offset:16
	s_add_u32 s0, s0, 16
	s_addc_u32 s1, s1, 0
	v_add_u32_e32 v18, 32, v18
	v_add_u32_e32 v4, 64, v4
	s_waitcnt vmcnt(19)
	v_mov_b32_e32 v176, v144
	s_waitcnt vmcnt(18)
	v_mov_b32_e32 v177, v148
	v_mov_b32_e32 v148, v145
	v_mov_b32_e32 v144, v146
	v_mov_b32_e32 v145, v150
	v_mov_b32_e32 v150, v147
	s_waitcnt vmcnt(16) lgkmcnt(3)
	v_pk_mul_f32 v[146:147], v[152:153], v[162:163] op_sel:[1,0] op_sel_hi:[0,0]
	v_pk_fma_f32 v[162:163], v[152:153], v[160:161], v[146:147] neg_lo:[0,0,1] neg_hi:[0,0,1]
	v_pk_fma_f32 v[146:147], v[152:153], v[160:161], v[146:147] op_sel_hi:[1,0,1]
	s_waitcnt vmcnt(15)
	v_pk_mul_f32 v[152:153], v[154:155], v[168:169] op_sel:[1,0] op_sel_hi:[0,0]
	s_waitcnt vmcnt(14) lgkmcnt(2)
	v_pk_mul_f32 v[160:161], v[156:157], v[170:171] op_sel:[1,0] op_sel_hi:[0,0]
	v_mov_b32_e32 v163, v147
	s_waitcnt vmcnt(12)
	v_pk_fma_f32 v[146:147], v[154:155], v[174:175], v[152:153] neg_lo:[0,0,1] neg_hi:[0,0,1]
	v_pk_fma_f32 v[152:153], v[154:155], v[174:175], v[152:153] op_sel_hi:[1,0,1]
	v_pk_mul_f32 v[168:169], v[158:159], v[172:173] op_sel:[1,0] op_sel_hi:[0,0]
	s_waitcnt vmcnt(11)
	v_pk_fma_f32 v[154:155], v[156:157], v[164:165], v[160:161] neg_lo:[0,0,1] neg_hi:[0,0,1]
	v_pk_fma_f32 v[156:157], v[156:157], v[164:165], v[160:161] op_sel_hi:[1,0,1]
	v_pk_mul_f32 v[162:163], v[176:177], v[162:163]
	v_mov_b32_e32 v147, v153
	s_waitcnt vmcnt(10)
	v_pk_fma_f32 v[160:161], v[158:159], v[166:167], v[168:169] neg_lo:[0,0,1] neg_hi:[0,0,1]
	v_pk_fma_f32 v[158:159], v[158:159], v[166:167], v[168:169] op_sel_hi:[1,0,1]
	v_mov_b32_e32 v155, v157
	v_sub_f32_e32 v5, v162, v163
	v_pk_mul_f32 v[146:147], v[148:149], v[146:147]
	v_mov_b32_e32 v161, v159
	v_pk_mul_f32 v[144:145], v[144:145], v[154:155]
	v_add_f32_e32 v0, v0, v5
	v_sub_f32_e32 v5, v146, v147
	v_pk_mul_f32 v[148:149], v[150:151], v[160:161]
	v_sub_f32_e32 v19, v144, v145
	v_add_f32_e32 v0, v0, v5
	v_sub_f32_e32 v144, v148, v149
	v_add_f32_e32 v0, v0, v19
	v_add_f32_e32 v0, v0, v144
	s_sub_i32 s32, s32, 1
	s_cmp_lg_u32 s32, 0
	s_cbranch_scc1 .Lp0_ktab_loop
; DI float2 cmul(float2 a, float2 b) { return make_float2(a.x * b.x - a.y * b.y, a.x * b.y + a.y * b.x); }
; DI void phase0(const Params& P, char* smem) {
;     ...
;       int h = tid >> 4, hp = tid & 15;
;       float s = 0.f;
;       for (int p = 0; p < 64; ++p) {
;         float2 T = cmul(Es[p], make_float2(P.b_re[(g * 64 + p) * 16 + hp], P.b_im[(g * 64 + p) * 16 + hp]));
;         s += P.c_re[(g * 16 + h) * 64 + p] * T.x - P.c_im[(g * 16 + h) * 64 + p] * T.y;
;       }
;       Ktab[((g * 64 + d) * 16 + h) * 16 + hp] = s;
;       __syncthreads();
	v_ashrrev_i32_e32 v5, 31, v4
	v_lshlrev_b64 v[158:159], 2, v[4:5]
	v_lshl_add_u64 v[144:145], v[2:3], 0, s[0:1]
	v_lshl_add_u64 v[148:149], v[6:7], 0, s[0:1]
	v_lshl_add_u64 v[160:161], s[62:63], 0, v[158:159]
	v_add_u32_e32 v152, 16, v4
	v_add_u32_e32 v154, 32, v4
	v_add_u32_e32 v156, 48, v4
	global_load_dwordx4 v[144:147], v[144:145], off
	s_nop 0
	global_load_dwordx4 v[148:151], v[148:149], off
	v_lshl_add_u64 v[158:159], s[64:65], 0, v[158:159]
	global_load_dword v160, v[160:161], off
	s_nop 0
	global_load_dword v162, v[158:159], off
	v_ashrrev_i32_e32 v153, 31, v152
	v_ashrrev_i32_e32 v155, 31, v154
	v_ashrrev_i32_e32 v157, 31, v156
	v_lshlrev_b64 v[152:153], 2, v[152:153]
	v_lshlrev_b64 v[154:155], 2, v[154:155]
	v_lshlrev_b64 v[156:157], 2, v[156:157]
	v_lshl_add_u64 v[158:159], s[62:63], 0, v[152:153]
	v_lshl_add_u64 v[152:153], s[64:65], 0, v[152:153]
	v_lshl_add_u64 v[164:165], s[62:63], 0, v[154:155]
	v_lshl_add_u64 v[166:167], s[62:63], 0, v[156:157]
	v_lshl_add_u64 v[154:155], s[64:65], 0, v[154:155]
	v_lshl_add_u64 v[156:157], s[64:65], 0, v[156:157]
	global_load_dword v168, v[152:153], off
	global_load_dword v170, v[154:155], off
	global_load_dword v172, v[156:157], off
	global_load_dword v174, v[158:159], off
	s_nop 0
	global_load_dword v164, v[164:165], off
	s_nop 0
	global_load_dword v166, v[166:167], off
	ds_read_b128 v[152:155], v18
	ds_read_b128 v[156:159], v18 offset:16
	s_add_u32 s0, s0, 16
	s_addc_u32 s1, s1, 0
	v_add_u32_e32 v18, 32, v18
	v_add_u32_e32 v4, 64, v4
	s_waitcnt vmcnt(19)
	v_mov_b32_e32 v52, v20
	s_waitcnt vmcnt(18)
	v_mov_b32_e32 v53, v24
	v_mov_b32_e32 v24, v21
	v_mov_b32_e32 v20, v22
	v_mov_b32_e32 v21, v26
	v_mov_b32_e32 v26, v23
	s_waitcnt vmcnt(16) lgkmcnt(3)
	v_pk_mul_f32 v[22:23], v[28:29], v[38:39] op_sel:[1,0] op_sel_hi:[0,0]
	v_pk_fma_f32 v[38:39], v[28:29], v[36:37], v[22:23] neg_lo:[0,0,1] neg_hi:[0,0,1]
	v_pk_fma_f32 v[22:23], v[28:29], v[36:37], v[22:23] op_sel_hi:[1,0,1]
	s_waitcnt vmcnt(15)
	v_pk_mul_f32 v[28:29], v[30:31], v[44:45] op_sel:[1,0] op_sel_hi:[0,0]
	s_waitcnt vmcnt(14) lgkmcnt(2)
	v_pk_mul_f32 v[36:37], v[32:33], v[46:47] op_sel:[1,0] op_sel_hi:[0,0]
	v_mov_b32_e32 v39, v23
	s_waitcnt vmcnt(12)
	v_pk_fma_f32 v[22:23], v[30:31], v[50:51], v[28:29] neg_lo:[0,0,1] neg_hi:[0,0,1]
	v_pk_fma_f32 v[28:29], v[30:31], v[50:51], v[28:29] op_sel_hi:[1,0,1]
	v_pk_mul_f32 v[44:45], v[34:35], v[48:49] op_sel:[1,0] op_sel_hi:[0,0]
	s_waitcnt vmcnt(11)
	v_pk_fma_f32 v[30:31], v[32:33], v[40:41], v[36:37] neg_lo:[0,0,1] neg_hi:[0,0,1]
	v_pk_fma_f32 v[32:33], v[32:33], v[40:41], v[36:37] op_sel_hi:[1,0,1]
	v_pk_mul_f32 v[38:39], v[52:53], v[38:39]
	v_mov_b32_e32 v23, v29
	s_waitcnt vmcnt(10)
	v_pk_fma_f32 v[36:37], v[34:35], v[42:43], v[44:45] neg_lo:[0,0,1] neg_hi:[0,0,1]
	v_pk_fma_f32 v[34:35], v[34:35], v[42:43], v[44:45] op_sel_hi:[1,0,1]
	v_mov_b32_e32 v31, v33
	v_sub_f32_e32 v5, v38, v39
	v_pk_mul_f32 v[22:23], v[24:25], v[22:23]
	v_mov_b32_e32 v37, v35
	v_pk_mul_f32 v[20:21], v[20:21], v[30:31]
	v_add_f32_e32 v0, v0, v5
	v_sub_f32_e32 v5, v22, v23
	v_pk_mul_f32 v[24:25], v[26:27], v[36:37]
	v_sub_f32_e32 v19, v20, v21
	v_add_f32_e32 v0, v0, v5
	v_sub_f32_e32 v20, v24, v25
	v_add_f32_e32 v0, v0, v19
	v_add_f32_e32 v0, v0, v20
	s_waitcnt vmcnt(9)
	v_mov_b32_e32 v176, v144
	s_waitcnt vmcnt(8)
	v_mov_b32_e32 v177, v148
	v_mov_b32_e32 v148, v145
	v_mov_b32_e32 v144, v146
	v_mov_b32_e32 v145, v150
	v_mov_b32_e32 v150, v147
	s_waitcnt vmcnt(6) lgkmcnt(1)
	v_pk_mul_f32 v[146:147], v[152:153], v[162:163] op_sel:[1,0] op_sel_hi:[0,0]
	v_pk_fma_f32 v[162:163], v[152:153], v[160:161], v[146:147] neg_lo:[0,0,1] neg_hi:[0,0,1]
	v_pk_fma_f32 v[146:147], v[152:153], v[160:161], v[146:147] op_sel_hi:[1,0,1]
	s_waitcnt vmcnt(5)
	v_pk_mul_f32 v[152:153], v[154:155], v[168:169] op_sel:[1,0] op_sel_hi:[0,0]
	s_waitcnt vmcnt(4) lgkmcnt(0)
	v_pk_mul_f32 v[160:161], v[156:157], v[170:171] op_sel:[1,0] op_sel_hi:[0,0]
	v_mov_b32_e32 v163, v147
	s_waitcnt vmcnt(2)
	v_pk_fma_f32 v[146:147], v[154:155], v[174:175], v[152:153] neg_lo:[0,0,1] neg_hi:[0,0,1]
	v_pk_fma_f32 v[152:153], v[154:155], v[174:175], v[152:153] op_sel_hi:[1,0,1]
	v_pk_mul_f32 v[168:169], v[158:159], v[172:173] op_sel:[1,0] op_sel_hi:[0,0]
	s_waitcnt vmcnt(1)
	v_pk_fma_f32 v[154:155], v[156:157], v[164:165], v[160:161] neg_lo:[0,0,1] neg_hi:[0,0,1]
	v_pk_fma_f32 v[156:157], v[156:157], v[164:165], v[160:161] op_sel_hi:[1,0,1]
	v_pk_mul_f32 v[162:163], v[176:177], v[162:163]
	v_mov_b32_e32 v147, v153
	s_waitcnt vmcnt(0)
	v_pk_fma_f32 v[160:161], v[158:159], v[166:167], v[168:169] neg_lo:[0,0,1] neg_hi:[0,0,1]
	v_pk_fma_f32 v[158:159], v[158:159], v[166:167], v[168:169] op_sel_hi:[1,0,1]
	v_mov_b32_e32 v155, v157
	v_sub_f32_e32 v5, v162, v163
	v_pk_mul_f32 v[146:147], v[148:149], v[146:147]
	v_mov_b32_e32 v161, v159
	v_pk_mul_f32 v[144:145], v[144:145], v[154:155]
	v_add_f32_e32 v0, v0, v5
	v_sub_f32_e32 v5, v146, v147
	v_pk_mul_f32 v[148:149], v[150:151], v[160:161]
	v_sub_f32_e32 v19, v144, v145
	v_add_f32_e32 v0, v0, v5
	v_sub_f32_e32 v144, v148, v149
	v_add_f32_e32 v0, v0, v19
	v_add_f32_e32 v0, v0, v144
	v_lshl_or_b32 v2, v17, 8, v191
	v_ashrrev_i32_e32 v3, 31, v2
	s_add_i32 s70, s70, s14
	v_lshl_add_u64 v[2:3], v[2:3], 2, s[16:17]
	s_cmpk_gt_i32 s70, 0x7ff
	v_add_u32_e32 v16, s14, v16
	global_store_dword v[2:3], v0, off
	s_barrier
	s_cbranch_scc0 .LBB0_36
